# P1/P4 GEMM tile epilogues: static s_setprio 1 for waves 4-7 at epilogue start
# baseline (speedup 1.0000x reference)
; #define PG8_STAGE(bufoff, gbase, voff) do { _Pragma("unroll") for (int _i = 0; _i < 2; ++_i) \
;         __builtin_amdgcn_global_load_lds((const unsigned*)((const char*)(gbase) + (voff)[_i]), (LAS unsigned*)(lds + (bufoff) + ldsw + _i * 8192), 16, 0, 0); } while (0)
; #define PG8_LDA(dst, b, h) do { _Pragma("unroll") for (int m = 0; m < 4; ++m) _Pragma("unroll") for (int k = 0; k < 2; ++k) dst[m][k] = *(const LAS bf16x8*)(lds + PG8_SA(b, h) + aoff + m * 2048 + k * 1024); } while (0)
; #define PG8_LDB(dst, b, h) do { _Pragma("unroll") for (int n = 0; n < 2; ++n) _Pragma("unroll") for (int k = 0; k < 2; ++k) dst[n][k] = *(const LAS bf16x8*)(lds + PG8_SB(b, h) + boff + n * 2048 + k * 1024); } while (0)
; #define PG8_MMA(ai, bj, At, Bt) do { __builtin_amdgcn_s_setprio(1); _Pragma("unroll") for (int m = 0; m < 4; ++m) _Pragma("unroll") for (int n = 0; n < 2; ++n) _Pragma("unroll") for (int k = 0; k < 2; ++k) \
;         acc[ai][bj][m][n] = __builtin_amdgcn_mfma_f32_16x16x32_bf16(Bt[n][k], At[m][k], acc[ai][bj][m][n], 0, 0, 0); __builtin_amdgcn_s_setprio(0); } while (0)
; #define PG8_WAIT_L(n) asm volatile("s_waitcnt lgkmcnt(" #n ")" ::: "memory")
; #define PG8_BAR __builtin_amdgcn_s_barrier()
; #define PG8_SCHED __builtin_amdgcn_sched_barrier(0)
; #define PG8_LDA(dst, b, h) do { _Pragma("unroll") for (int m = 0; m < 4; ++m) _Pragma("unroll") for (int k = 0; k < 2; ++k) dst[m][k] = *(const LAS bf16x8*)(lds + PG8_SA(b, h) + aoff + m * 2048 + k * 1024); } while (0)
; #define PG8_LDB(dst, b, h) do { _Pragma("unroll") for (int n = 0; n < 2; ++n) _Pragma("unroll") for (int k = 0; k < 2; ++k) dst[n][k] = *(const LAS bf16x8*)(lds + PG8_SB(b, h) + boff + n * 2048 + k * 1024); } while (0)
; template <class Epi, bool AFTER = false>
; __device__ __forceinline__ void gemm_phase(LAS unsigned char* lds, const Gemm g, const StaticOrder& S, const Epi& E) {
;     ...
;             PG8_LDB(B0, 0, 0); PG8_SCHED; PG8_LDA(At, 0, 0); PG8_STAGE(PG8_SA(1, 1), a1 + hstep, voffA);
;             PG8_WAIT_L(8); PG8_BAR; PG8_WAIT_L(0); PG8_MMA(0, 0, At, B0); PG8_BAR; PG8_SCHED;
;             PG8_LDB(B1, 0, 1); PG8_STAGE(PG8_SB(0, 0), b2, voffB);
;             PG8_BAR; PG8_WAIT_L(0); PG8_MMA(0, 1, At, B1); PG8_BAR;
;             PG8_LDA(At, 0, 1); PG8_STAGE(PG8_SA(0, 0), a2, voffA);
;             PG8_BAR; PG8_WAIT_L(0); PG8_MMA(1, 0, At, B0); PG8_BAR; PG8_SCHED;
.LBB0_118:
	ds_read_b128 v[150:153], v147
	ds_read_b128 v[154:157], v147 offset:1024
	ds_read_b128 v[158:161], v147 offset:2048
	ds_read_b128 v[162:165], v147 offset:3072
	s_add_u32 s18, s16, 0xfffc0080
	s_addc_u32 s19, s17, -1
	s_cmp_eq_u32 s43, 12
	s_cselect_b32 s21, s11, s19
	s_cselect_b32 s20, s39, s18
	s_cselect_b32 s19, s9, s42
	s_cselect_b32 s18, s40, s41
	v_lshl_add_u64 v[200:201], s[16:17], 0, v[136:137]
	s_add_i32 m0, s7, 0xc000
	ds_read_b128 v[166:169], v148
	ds_read_b128 v[170:173], v148 offset:1024
	ds_read_b128 v[174:177], v148 offset:2048
	ds_read_b128 v[178:181], v148 offset:3072
	ds_read_b128 v[182:185], v148 offset:4096
	ds_read_b128 v[186:189], v148 offset:5120
	ds_read_b128 v[192:195], v148 offset:6144
	ds_read_b128 v[196:199], v148 offset:7168
	global_load_lds_dwordx4 v[200:201], off
	v_lshl_add_u64 v[200:201], s[16:17], 0, v[138:139]
	s_add_i32 m0, s7, 0xe000
	s_nop 0
	global_load_lds_dwordx4 v[200:201], off
	s_waitcnt lgkmcnt(8)
	s_barrier
	s_waitcnt lgkmcnt(0)
	s_setprio 1
	s_waitcnt lgkmcnt(0)
	v_mfma_f32_16x16x32_bf16 v[124:127], v[150:153], v[166:169], v[124:127]
	v_mfma_f32_16x16x32_bf16 v[120:123], v[158:161], v[166:169], v[120:123]
	v_mfma_f32_16x16x32_bf16 v[116:119], v[150:153], v[174:177], v[116:119]
	v_mfma_f32_16x16x32_bf16 v[112:115], v[158:161], v[174:177], v[112:115]
	v_mfma_f32_16x16x32_bf16 v[100:103], v[150:153], v[182:185], v[100:103]
	v_mfma_f32_16x16x32_bf16 v[96:99], v[158:161], v[182:185], v[96:99]
	v_mfma_f32_16x16x32_bf16 v[84:87], v[150:153], v[192:195], v[84:87]
	v_mfma_f32_16x16x32_bf16 v[80:83], v[158:161], v[192:195], v[80:83]
	v_mfma_f32_16x16x32_bf16 v[124:127], v[154:157], v[170:173], v[124:127]
	v_mfma_f32_16x16x32_bf16 v[120:123], v[162:165], v[170:173], v[120:123]
	v_mfma_f32_16x16x32_bf16 v[116:119], v[154:157], v[178:181], v[116:119]
	v_mfma_f32_16x16x32_bf16 v[112:115], v[162:165], v[178:181], v[112:115]
	v_mfma_f32_16x16x32_bf16 v[100:103], v[154:157], v[186:189], v[100:103]
	v_mfma_f32_16x16x32_bf16 v[96:99], v[162:165], v[186:189], v[96:99]
	v_mfma_f32_16x16x32_bf16 v[84:87], v[154:157], v[196:199], v[84:87]
	v_mfma_f32_16x16x32_bf16 v[80:83], v[162:165], v[196:199], v[80:83]
	s_setprio 0
	s_barrier
	s_add_i32 s44, s35, s23
	v_lshl_add_u64 v[218:219], s[18:19], 0, v[130:131]
	s_mov_b32 m0, s44
	ds_read_b128 v[200:203], v149
	ds_read_b128 v[204:207], v149 offset:1024
	ds_read_b128 v[208:211], v149 offset:2048
	ds_read_b128 v[214:217], v149 offset:3072
	global_load_lds_dwordx4 v[218:219], off
	v_lshl_add_u64 v[220:221], s[18:19], 0, v[134:135]
	s_add_i32 m0, s44, 0x2000
	s_nop 0
	global_load_lds_dwordx4 v[220:221], off
	s_barrier
	s_waitcnt lgkmcnt(0)
	s_setprio 1
	s_waitcnt lgkmcnt(0)
	v_mfma_f32_16x16x32_bf16 v[108:111], v[200:203], v[166:169], v[108:111]
	v_mfma_f32_16x16x32_bf16 v[104:107], v[208:211], v[166:169], v[104:107]
	v_mfma_f32_16x16x32_bf16 v[92:95], v[200:203], v[174:177], v[92:95]
	v_mfma_f32_16x16x32_bf16 v[88:91], v[208:211], v[174:177], v[88:91]
	v_mfma_f32_16x16x32_bf16 v[76:79], v[200:203], v[182:185], v[76:79]
	v_mfma_f32_16x16x32_bf16 v[72:75], v[208:211], v[182:185], v[72:75]
	v_mfma_f32_16x16x32_bf16 v[68:71], v[200:203], v[192:195], v[68:71]
	v_mfma_f32_16x16x32_bf16 v[64:67], v[208:211], v[192:195], v[64:67]
	v_mfma_f32_16x16x32_bf16 v[108:111], v[204:207], v[170:173], v[108:111]
	v_mfma_f32_16x16x32_bf16 v[104:107], v[214:217], v[170:173], v[104:107]
	v_mfma_f32_16x16x32_bf16 v[92:95], v[204:207], v[178:181], v[92:95]
	v_mfma_f32_16x16x32_bf16 v[88:91], v[214:217], v[178:181], v[88:91]
	v_mfma_f32_16x16x32_bf16 v[76:79], v[204:207], v[186:189], v[76:79]
	v_mfma_f32_16x16x32_bf16 v[72:75], v[214:217], v[186:189], v[72:75]
	v_mfma_f32_16x16x32_bf16 v[68:71], v[204:207], v[196:199], v[68:71]
	v_mfma_f32_16x16x32_bf16 v[64:67], v[214:217], v[196:199], v[64:67]
	s_setprio 0
	s_mov_b32 m0, s7
	v_lshl_add_u64 v[222:223], s[20:21], 0, v[128:129]
	s_barrier
	ds_read_b128 v[166:169], v148 offset:16384
	ds_read_b128 v[170:173], v148 offset:17408
	ds_read_b128 v[174:177], v148 offset:18432
	ds_read_b128 v[178:181], v148 offset:19456
	ds_read_b128 v[182:185], v148 offset:20480
	ds_read_b128 v[186:189], v148 offset:21504
	ds_read_b128 v[192:195], v148 offset:22528
	ds_read_b128 v[196:199], v148 offset:23552
	global_load_lds_dwordx4 v[222:223], off
	v_lshl_add_u64 v[224:225], s[20:21], 0, v[132:133]
	s_mov_b32 m0, s26
	s_nop 0
	global_load_lds_dwordx4 v[224:225], off
	s_barrier
	s_waitcnt lgkmcnt(0)
	s_setprio 1
	s_waitcnt lgkmcnt(0)
	v_mfma_f32_16x16x32_bf16 v[60:63], v[150:153], v[166:169], v[60:63]
	v_mfma_f32_16x16x32_bf16 v[56:59], v[158:161], v[166:169], v[56:59]
	v_mfma_f32_16x16x32_bf16 v[52:55], v[150:153], v[174:177], v[52:55]
	v_mfma_f32_16x16x32_bf16 v[48:51], v[158:161], v[174:177], v[48:51]
	v_mfma_f32_16x16x32_bf16 v[36:39], v[150:153], v[182:185], v[36:39]
	v_mfma_f32_16x16x32_bf16 v[32:35], v[158:161], v[182:185], v[32:35]
	v_mfma_f32_16x16x32_bf16 v[20:23], v[150:153], v[192:195], v[20:23]
	v_mfma_f32_16x16x32_bf16 v[16:19], v[158:161], v[192:195], v[16:19]
	v_mfma_f32_16x16x32_bf16 v[60:63], v[154:157], v[170:173], v[60:63]
	v_mfma_f32_16x16x32_bf16 v[56:59], v[162:165], v[170:173], v[56:59]
	v_mfma_f32_16x16x32_bf16 v[52:55], v[154:157], v[178:181], v[52:55]
	v_mfma_f32_16x16x32_bf16 v[48:51], v[162:165], v[178:181], v[48:51]
	v_mfma_f32_16x16x32_bf16 v[36:39], v[154:157], v[186:189], v[36:39]
	v_mfma_f32_16x16x32_bf16 v[32:35], v[162:165], v[186:189], v[32:35]
	v_mfma_f32_16x16x32_bf16 v[20:23], v[154:157], v[196:199], v[20:23]
	v_mfma_f32_16x16x32_bf16 v[16:19], v[162:165], v[196:199], v[16:19]
	s_setprio 0
	s_barrier
; #define PG8_STAGE(bufoff, gbase, voff) do { _Pragma("unroll") for (int _i = 0; _i < 2; ++_i) \
;         __builtin_amdgcn_global_load_lds((const unsigned*)((const char*)(gbase) + (voff)[_i]), (LAS unsigned*)(lds + (bufoff) + ldsw + _i * 8192), 16, 0, 0); } while (0)
; #define PG8_LDA(dst, b, h) do { _Pragma("unroll") for (int m = 0; m < 4; ++m) _Pragma("unroll") for (int k = 0; k < 2; ++k) dst[m][k] = *(const LAS bf16x8*)(lds + PG8_SA(b, h) + aoff + m * 2048 + k * 1024); } while (0)
; #define PG8_LDB(dst, b, h) do { _Pragma("unroll") for (int n = 0; n < 2; ++n) _Pragma("unroll") for (int k = 0; k < 2; ++k) dst[n][k] = *(const LAS bf16x8*)(lds + PG8_SB(b, h) + boff + n * 2048 + k * 1024); } while (0)
; #define PG8_MMA(ai, bj, At, Bt) do { __builtin_amdgcn_s_setprio(1); _Pragma("unroll") for (int m = 0; m < 4; ++m) _Pragma("unroll") for (int n = 0; n < 2; ++n) _Pragma("unroll") for (int k = 0; k < 2; ++k) \
;         acc[ai][bj][m][n] = __builtin_amdgcn_mfma_f32_16x16x32_bf16(Bt[n][k], At[m][k], acc[ai][bj][m][n], 0, 0, 0); __builtin_amdgcn_s_setprio(0); } while (0)
; #define PG8_WAIT_V(n) asm volatile("s_waitcnt vmcnt(" #n ")" ::: "memory")
; #define PG8_WAIT_L(n) asm volatile("s_waitcnt lgkmcnt(" #n ")" ::: "memory")
; #define PG8_BAR __builtin_amdgcn_s_barrier()
; #define PG8_SCHED __builtin_amdgcn_sched_barrier(0)
; #define PG8_LDA(dst, b, h) do { _Pragma("unroll") for (int m = 0; m < 4; ++m) _Pragma("unroll") for (int k = 0; k < 2; ++k) dst[m][k] = *(const LAS bf16x8*)(lds + PG8_SA(b, h) + aoff + m * 2048 + k * 1024); } while (0)
; #define PG8_BAR __builtin_amdgcn_s_barrier()
; template <class Epi, bool AFTER = false>
; __device__ __forceinline__ void gemm_phase(LAS unsigned char* lds, const Gemm g, const StaticOrder& S, const Epi& E) {
;     ...
;             PG8_STAGE(PG8_SB(0, 1), b2 + hstep, voffB);
;             PG8_WAIT_V(6); PG8_BAR; PG8_MMA(1, 1, At, B1); PG8_BAR;
;             PG8_LDB(B0, 1, 0); PG8_SCHED; PG8_LDA(At, 1, 0); PG8_STAGE(PG8_SA(0, 1), a2 + hstep, voffA);
;             PG8_WAIT_L(8); PG8_BAR; PG8_WAIT_L(0); PG8_MMA(0, 0, At, B0); PG8_BAR; PG8_SCHED;
;             PG8_LDB(B1, 1, 1); PG8_STAGE(PG8_SB(1, 0), b3, voffB);
;             PG8_BAR; PG8_WAIT_L(0); PG8_MMA(0, 1, At, B1); PG8_BAR;
;             PG8_LDA(At, 1, 1); PG8_STAGE(PG8_SA(1, 0), a3, voffA);
;             PG8_BAR; PG8_WAIT_L(0); PG8_MMA(1, 0, At, B0); PG8_BAR; PG8_SCHED;
	s_add_u32 s44, s18, 0x40000
	s_addc_u32 s45, s19, 0
	s_add_i32 s46, s36, s23
	v_lshl_add_u64 v[150:151], s[44:45], 0, v[130:131]
	s_mov_b32 m0, s46
	s_nop 0
	global_load_lds_dwordx4 v[150:151], off
	v_lshl_add_u64 v[150:151], s[44:45], 0, v[134:135]
	s_add_i32 m0, s46, 0x2000
	s_nop 0
	global_load_lds_dwordx4 v[150:151], off
	s_waitcnt vmcnt(6)
	s_barrier
	s_setprio 1
	v_mfma_f32_16x16x32_bf16 v[44:47], v[200:203], v[166:169], v[44:47]
	v_mfma_f32_16x16x32_bf16 v[40:43], v[208:211], v[166:169], v[40:43]
	v_mfma_f32_16x16x32_bf16 v[28:31], v[200:203], v[174:177], v[28:31]
	v_mfma_f32_16x16x32_bf16 v[24:27], v[208:211], v[174:177], v[24:27]
	v_mfma_f32_16x16x32_bf16 v[12:15], v[200:203], v[182:185], v[12:15]
	v_mfma_f32_16x16x32_bf16 v[8:11], v[208:211], v[182:185], v[8:11]
	v_mfma_f32_16x16x32_bf16 v[4:7], v[200:203], v[192:195], v[4:7]
	v_mfma_f32_16x16x32_bf16 v[0:3], v[208:211], v[192:195], v[0:3]
	v_mfma_f32_16x16x32_bf16 v[44:47], v[204:207], v[170:173], v[44:47]
	v_mfma_f32_16x16x32_bf16 v[40:43], v[214:217], v[170:173], v[40:43]
	v_mfma_f32_16x16x32_bf16 v[28:31], v[204:207], v[178:181], v[28:31]
	v_mfma_f32_16x16x32_bf16 v[24:27], v[214:217], v[178:181], v[24:27]
	v_mfma_f32_16x16x32_bf16 v[12:15], v[204:207], v[186:189], v[12:15]
	v_mfma_f32_16x16x32_bf16 v[8:11], v[214:217], v[186:189], v[8:11]
	v_mfma_f32_16x16x32_bf16 v[4:7], v[204:207], v[196:199], v[4:7]
	v_mfma_f32_16x16x32_bf16 v[0:3], v[214:217], v[196:199], v[0:3]
	s_setprio 0
	s_add_i32 s44, 0, 0x18000
	v_add_u32_e32 v162, s44, v145
	s_barrier
	ds_read_b128 v[150:153], v162
	ds_read_b128 v[154:157], v162 offset:1024
	ds_read_b128 v[158:161], v162 offset:2048
	ds_read_b128 v[162:165], v162 offset:3072
	s_add_u32 s20, s20, 0x40000
	s_addc_u32 s21, s21, 0
	s_mov_b32 m0, s27
	v_lshl_add_u64 v[200:201], s[20:21], 0, v[128:129]
	ds_read_b128 v[166:169], v148 offset:32768
	ds_read_b128 v[170:173], v148 offset:33792
	ds_read_b128 v[174:177], v148 offset:34816
	ds_read_b128 v[178:181], v148 offset:35840
	ds_read_b128 v[182:185], v148 offset:36864
	ds_read_b128 v[186:189], v148 offset:37888
	ds_read_b128 v[192:195], v148 offset:38912
	ds_read_b128 v[196:199], v148 offset:39936
	global_load_lds_dwordx4 v[200:201], off
	v_lshl_add_u64 v[200:201], s[20:21], 0, v[132:133]
	s_mov_b32 m0, s28
	s_nop 0
	global_load_lds_dwordx4 v[200:201], off
	s_waitcnt lgkmcnt(8)
	s_barrier
	s_waitcnt lgkmcnt(0)
	s_setprio 1
	s_waitcnt lgkmcnt(0)
	v_mfma_f32_16x16x32_bf16 v[124:127], v[150:153], v[166:169], v[124:127]
	v_mfma_f32_16x16x32_bf16 v[120:123], v[158:161], v[166:169], v[120:123]
	v_mfma_f32_16x16x32_bf16 v[116:119], v[150:153], v[174:177], v[116:119]
	v_mfma_f32_16x16x32_bf16 v[112:115], v[158:161], v[174:177], v[112:115]
	v_mfma_f32_16x16x32_bf16 v[100:103], v[150:153], v[182:185], v[100:103]
	v_mfma_f32_16x16x32_bf16 v[96:99], v[158:161], v[182:185], v[96:99]
	v_mfma_f32_16x16x32_bf16 v[84:87], v[150:153], v[192:195], v[84:87]
	v_mfma_f32_16x16x32_bf16 v[80:83], v[158:161], v[192:195], v[80:83]
	v_mfma_f32_16x16x32_bf16 v[124:127], v[154:157], v[170:173], v[124:127]
	v_mfma_f32_16x16x32_bf16 v[120:123], v[162:165], v[170:173], v[120:123]
	v_mfma_f32_16x16x32_bf16 v[116:119], v[154:157], v[178:181], v[116:119]
	v_mfma_f32_16x16x32_bf16 v[112:115], v[162:165], v[178:181], v[112:115]
	v_mfma_f32_16x16x32_bf16 v[100:103], v[154:157], v[186:189], v[100:103]
	v_mfma_f32_16x16x32_bf16 v[96:99], v[162:165], v[186:189], v[96:99]
	v_mfma_f32_16x16x32_bf16 v[84:87], v[154:157], v[196:199], v[84:87]
	v_mfma_f32_16x16x32_bf16 v[80:83], v[162:165], v[196:199], v[80:83]
	s_setprio 0
	s_barrier
	s_add_i32 s20, 0, 0x1c000
	s_add_i32 s21, s44, s23
	v_add_u32_e32 v191, s20, v145
	v_lshl_add_u64 v[218:219], v[218:219], 0, s[4:5]
	s_mov_b32 m0, s21
	ds_read_b128 v[200:203], v191
	ds_read_b128 v[204:207], v191 offset:1024
	ds_read_b128 v[208:211], v191 offset:2048
	ds_read_b128 v[214:217], v191 offset:3072
	global_load_lds_dwordx4 v[218:219], off
	v_lshl_add_u64 v[218:219], v[220:221], 0, s[4:5]
	s_add_i32 m0, s21, 0x2000
	s_nop 0
	global_load_lds_dwordx4 v[218:219], off
	s_barrier
	s_waitcnt lgkmcnt(0)
	s_setprio 1
	s_waitcnt lgkmcnt(0)
	v_mfma_f32_16x16x32_bf16 v[108:111], v[200:203], v[166:169], v[108:111]
	v_mfma_f32_16x16x32_bf16 v[104:107], v[208:211], v[166:169], v[104:107]
	v_mfma_f32_16x16x32_bf16 v[92:95], v[200:203], v[174:177], v[92:95]
	v_mfma_f32_16x16x32_bf16 v[88:91], v[208:211], v[174:177], v[88:91]
	v_mfma_f32_16x16x32_bf16 v[76:79], v[200:203], v[182:185], v[76:79]
	v_mfma_f32_16x16x32_bf16 v[72:75], v[208:211], v[182:185], v[72:75]
	v_mfma_f32_16x16x32_bf16 v[68:71], v[200:203], v[192:195], v[68:71]
	v_mfma_f32_16x16x32_bf16 v[64:67], v[208:211], v[192:195], v[64:67]
	v_mfma_f32_16x16x32_bf16 v[108:111], v[204:207], v[170:173], v[108:111]
	v_mfma_f32_16x16x32_bf16 v[104:107], v[214:217], v[170:173], v[104:107]
	v_mfma_f32_16x16x32_bf16 v[92:95], v[204:207], v[178:181], v[92:95]
	v_mfma_f32_16x16x32_bf16 v[88:91], v[214:217], v[178:181], v[88:91]
	v_mfma_f32_16x16x32_bf16 v[76:79], v[204:207], v[186:189], v[76:79]
	v_mfma_f32_16x16x32_bf16 v[72:75], v[214:217], v[186:189], v[72:75]
	v_mfma_f32_16x16x32_bf16 v[68:71], v[204:207], v[196:199], v[68:71]
	v_mfma_f32_16x16x32_bf16 v[64:67], v[214:217], v[196:199], v[64:67]
	s_setprio 0
	s_mov_b32 m0, s31
	v_lshl_add_u64 v[218:219], v[222:223], 0, s[4:5]
	s_barrier
; __device__ __forceinline__ unsigned cvt_pk_bf16(float lo, float hi) { const f32x2_t f = {lo, hi}; const bf16x2_t b = __builtin_convertvector(f, bf16x2_t); return __builtin_bit_cast(unsigned, b); }
; __device__ __forceinline__ void st_wt16(void* p, u32x4 v) { asm volatile("global_store_dwordx4 %0, %1, off sc1\n\ts_nop 1" : : "v"(p), "v"(v) : "memory"); }
; __device__ __forceinline__ void st_wt16_o256(void* p, u32x4 v) { asm volatile("global_store_dwordx4 %0, %1, off offset:256 sc1\n\ts_nop 1" : : "v"(p), "v"(v) : "memory"); }
; #define PG8_STAGE(bufoff, gbase, voff) do { _Pragma("unroll") for (int _i = 0; _i < 2; ++_i) \
;         __builtin_amdgcn_global_load_lds((const unsigned*)((const char*)(gbase) + (voff)[_i]), (LAS unsigned*)(lds + (bufoff) + ldsw + _i * 8192), 16, 0, 0); } while (0)
; #define PG8_WAIT_V(n) asm volatile("s_waitcnt vmcnt(" #n ")" ::: "memory")
; #define PG8_BAR __builtin_amdgcn_s_barrier()
; #define PG8_WAIT_V(n) asm volatile("s_waitcnt vmcnt(" #n ")" ::: "memory")
; #define PG8_BAR __builtin_amdgcn_s_barrier()
; template <class Epi, bool AFTER = false>
; __device__ __forceinline__ void gemm_phase(LAS unsigned char* lds, const Gemm g, const StaticOrder& S, const Epi& E) {
;     ...
;             PG8_STAGE(PG8_SB(1, 1), b3 + hstep, voffB);
;             PG8_WAIT_V(6); PG8_BAR; PG8_MMA(1, 1, At, B1); PG8_BAR;
;         }
;         if constexpr (!AFTER) E(acc, cur, wr, wc, fr, fq);
;     __device__ __forceinline__ void operator()(const f32x4 (&acc)[2][2][4][2], const pg8::Unit& u, int wr, int wc, int fr, int fq) const {
;     ...
;                 bf16_t* rp = base + (size_t)(row0 + ai * 128 + m * 16) * ld + col0;
;                 u32x4 w0, w1;
;                 w0.x = cvt_pk_bf16(acc[ai][0][m][0][0], acc[ai][0][m][0][1]); w0.y = cvt_pk_bf16(acc[ai][0][m][0][2], acc[ai][0][m][0][3]);
;                 w0.z = cvt_pk_bf16(acc[ai][0][m][1][0], acc[ai][0][m][1][1]); w0.w = cvt_pk_bf16(acc[ai][0][m][1][2], acc[ai][0][m][1][3]);
;                 w1.x = cvt_pk_bf16(acc[ai][1][m][0][0], acc[ai][1][m][0][1]); w1.y = cvt_pk_bf16(acc[ai][1][m][0][2], acc[ai][1][m][0][3]);
;                 w1.z = cvt_pk_bf16(acc[ai][1][m][1][0], acc[ai][1][m][1][1]); w1.w = cvt_pk_bf16(acc[ai][1][m][1][2], acc[ai][1][m][1][3]);
;                 st_wt16(rp, w0); st_wt16_o256(rp, w1);
	ds_read_b128 v[166:169], v148 offset:49152
	ds_read_b128 v[170:173], v148 offset:50176
	ds_read_b128 v[174:177], v148 offset:51200
	ds_read_b128 v[178:181], v148 offset:52224
	ds_read_b128 v[182:185], v148 offset:53248
	ds_read_b128 v[186:189], v148 offset:54272
	ds_read_b128 v[192:195], v148 offset:55296
	ds_read_b128 v[196:199], v148 offset:56320
	global_load_lds_dwordx4 v[218:219], off
	v_lshl_add_u64 v[218:219], v[224:225], 0, s[4:5]
	s_mov_b32 m0, s33
	s_nop 0
	global_load_lds_dwordx4 v[218:219], off
	s_barrier
	s_waitcnt lgkmcnt(0)
	s_setprio 1
	s_waitcnt lgkmcnt(0)
	v_mfma_f32_16x16x32_bf16 v[60:63], v[150:153], v[166:169], v[60:63]
	v_mfma_f32_16x16x32_bf16 v[56:59], v[158:161], v[166:169], v[56:59]
	v_mfma_f32_16x16x32_bf16 v[52:55], v[150:153], v[174:177], v[52:55]
	v_mfma_f32_16x16x32_bf16 v[48:51], v[158:161], v[174:177], v[48:51]
	v_mfma_f32_16x16x32_bf16 v[36:39], v[150:153], v[182:185], v[36:39]
	v_mfma_f32_16x16x32_bf16 v[32:35], v[158:161], v[182:185], v[32:35]
	v_mfma_f32_16x16x32_bf16 v[20:23], v[150:153], v[192:195], v[20:23]
	v_mfma_f32_16x16x32_bf16 v[16:19], v[158:161], v[192:195], v[16:19]
	v_mfma_f32_16x16x32_bf16 v[60:63], v[154:157], v[170:173], v[60:63]
	v_mfma_f32_16x16x32_bf16 v[56:59], v[162:165], v[170:173], v[56:59]
	v_mfma_f32_16x16x32_bf16 v[52:55], v[154:157], v[178:181], v[52:55]
	v_mfma_f32_16x16x32_bf16 v[48:51], v[162:165], v[178:181], v[48:51]
	v_mfma_f32_16x16x32_bf16 v[36:39], v[154:157], v[186:189], v[36:39]
	v_mfma_f32_16x16x32_bf16 v[32:35], v[162:165], v[186:189], v[32:35]
	v_mfma_f32_16x16x32_bf16 v[20:23], v[154:157], v[196:199], v[20:23]
	v_mfma_f32_16x16x32_bf16 v[16:19], v[162:165], v[196:199], v[16:19]
	s_setprio 0
	s_barrier
	s_add_u32 s18, s18, 0x40080
	s_addc_u32 s19, s19, 0
	s_add_i32 s20, s20, s23
	v_lshl_add_u64 v[150:151], s[18:19], 0, v[130:131]
	s_mov_b32 m0, s20
	s_nop 0
	global_load_lds_dwordx4 v[150:151], off
	v_lshl_add_u64 v[150:151], s[18:19], 0, v[134:135]
	s_add_i32 m0, s20, 0x2000
	s_nop 0
	global_load_lds_dwordx4 v[150:151], off
	s_waitcnt vmcnt(6)
	s_barrier
	s_setprio 1
	v_mfma_f32_16x16x32_bf16 v[44:47], v[200:203], v[166:169], v[44:47]
	v_mfma_f32_16x16x32_bf16 v[40:43], v[208:211], v[166:169], v[40:43]
	v_mfma_f32_16x16x32_bf16 v[28:31], v[200:203], v[174:177], v[28:31]
	v_mfma_f32_16x16x32_bf16 v[24:27], v[208:211], v[174:177], v[24:27]
	v_mfma_f32_16x16x32_bf16 v[12:15], v[200:203], v[182:185], v[12:15]
	v_mfma_f32_16x16x32_bf16 v[8:11], v[208:211], v[182:185], v[8:11]
	v_mfma_f32_16x16x32_bf16 v[4:7], v[200:203], v[192:195], v[4:7]
	v_mfma_f32_16x16x32_bf16 v[0:3], v[208:211], v[192:195], v[0:3]
	v_mfma_f32_16x16x32_bf16 v[44:47], v[204:207], v[170:173], v[44:47]
	v_mfma_f32_16x16x32_bf16 v[40:43], v[214:217], v[170:173], v[40:43]
	v_mfma_f32_16x16x32_bf16 v[28:31], v[204:207], v[178:181], v[28:31]
	v_mfma_f32_16x16x32_bf16 v[24:27], v[214:217], v[178:181], v[24:27]
	v_mfma_f32_16x16x32_bf16 v[12:15], v[204:207], v[186:189], v[12:15]
	v_mfma_f32_16x16x32_bf16 v[8:11], v[214:217], v[186:189], v[8:11]
	v_mfma_f32_16x16x32_bf16 v[4:7], v[204:207], v[196:199], v[4:7]
	v_mfma_f32_16x16x32_bf16 v[0:3], v[214:217], v[196:199], v[0:3]
	s_setprio 0
	s_add_i32 s43, s43, 2
	s_add_u32 s16, s16, 0x100
	s_addc_u32 s17, s17, 0
	s_add_u32 s41, s41, 0x100
	s_addc_u32 s42, s42, 0
	s_cmp_gt_u32 s43, 13
	s_barrier
	s_cbranch_scc0 .LBB0_118
	v_readfirstlane_b32 s101, v212
	s_nop 3
	s_cmp_ge_u32 s101, 0x100
	s_cbranch_scc0 .Lep_p1
	s_setprio 1
.Lep_p1:
	s_and_b64 vcc, exec, s[2:3]
	s_cbranch_vccnz .Lg1_fullepi
	v_lshl_or_b32 v226, s38, 8, v146
	v_readlane_b32 s16, v254, 20
	v_ashrrev_i32_e32 v227, 31, v226
	v_readlane_b32 s17, v254, 21
	v_lshl_add_u32 v228, s6, 8, v144
	s_nop 1
	v_lshl_add_u64 v[226:227], v[226:227], 1, s[16:17]
	v_mad_i64_i32 v[230:231], s[98:99], v228, s37, v[226:227]
	v_cvt_pk_bf16_f32 v124, v124, v125
	v_cvt_pk_bf16_f32 v125, v126, v127
	v_cvt_pk_bf16_f32 v126, v120, v121
	v_cvt_pk_bf16_f32 v127, v122, v123
	global_store_dwordx4 v[230:231], v[124:127], off sc1
	s_nop 1
	v_or_b32_e32 v229, 16, v228
	v_mad_i64_i32 v[232:233], s[98:99], v229, s37, v[226:227]
	v_cvt_pk_bf16_f32 v116, v116, v117
	v_cvt_pk_bf16_f32 v117, v118, v119
	v_cvt_pk_bf16_f32 v118, v112, v113
	v_cvt_pk_bf16_f32 v119, v114, v115
	global_store_dwordx4 v[232:233], v[116:119], off sc1
	s_nop 1
	v_or_b32_e32 v229, 32, v228
	v_mad_i64_i32 v[234:235], s[98:99], v229, s37, v[226:227]
	v_cvt_pk_bf16_f32 v100, v100, v101
	v_cvt_pk_bf16_f32 v101, v102, v103
	v_cvt_pk_bf16_f32 v102, v96, v97
	v_cvt_pk_bf16_f32 v103, v98, v99
	global_store_dwordx4 v[234:235], v[100:103], off sc1
	s_nop 1
	v_or_b32_e32 v229, 48, v228
	v_mad_i64_i32 v[236:237], s[98:99], v229, s37, v[226:227]
	v_cvt_pk_bf16_f32 v84, v84, v85
	v_cvt_pk_bf16_f32 v85, v86, v87
	v_cvt_pk_bf16_f32 v86, v80, v81
	v_cvt_pk_bf16_f32 v87, v82, v83
	global_store_dwordx4 v[236:237], v[84:87], off sc1
	s_nop 1
	s_mov_b32 s100, 1
	s_mov_b32 s38, s8
	s_mov_b32 s6, s10
	s_mov_b64 s[18:19], s[14:15]
	s_mov_b64 s[16:17], s[12:13]
	s_branch .LBB0_115

; #define PG8_STAGE(bufoff, gbase, voff) do { _Pragma("unroll") for (int _i = 0; _i < 2; ++_i) \
;         __builtin_amdgcn_global_load_lds((const unsigned*)((const char*)(gbase) + (voff)[_i]), (LAS unsigned*)(lds + (bufoff) + ldsw + _i * 8192), 16, 0, 0); } while (0)
; #define PG8_LDA(dst, b, h) do { _Pragma("unroll") for (int m = 0; m < 4; ++m) _Pragma("unroll") for (int k = 0; k < 2; ++k) dst[m][k] = *(const LAS bf16x8*)(lds + PG8_SA(b, h) + aoff + m * 2048 + k * 1024); } while (0)
; #define PG8_LDB(dst, b, h) do { _Pragma("unroll") for (int n = 0; n < 2; ++n) _Pragma("unroll") for (int k = 0; k < 2; ++k) dst[n][k] = *(const LAS bf16x8*)(lds + PG8_SB(b, h) + boff + n * 2048 + k * 1024); } while (0)
; #define PG8_MMA(ai, bj, At, Bt) do { __builtin_amdgcn_s_setprio(1); _Pragma("unroll") for (int m = 0; m < 4; ++m) _Pragma("unroll") for (int n = 0; n < 2; ++n) _Pragma("unroll") for (int k = 0; k < 2; ++k) \
;         acc[ai][bj][m][n] = __builtin_amdgcn_mfma_f32_16x16x32_bf16(Bt[n][k], At[m][k], acc[ai][bj][m][n], 0, 0, 0); __builtin_amdgcn_s_setprio(0); } while (0)
; #define PG8_WAIT_L(n) asm volatile("s_waitcnt lgkmcnt(" #n ")" ::: "memory")
; #define PG8_BAR __builtin_amdgcn_s_barrier()
; #define PG8_SCHED __builtin_amdgcn_sched_barrier(0)
; #define PG8_LDA(dst, b, h) do { _Pragma("unroll") for (int m = 0; m < 4; ++m) _Pragma("unroll") for (int k = 0; k < 2; ++k) dst[m][k] = *(const LAS bf16x8*)(lds + PG8_SA(b, h) + aoff + m * 2048 + k * 1024); } while (0)
; #define PG8_LDB(dst, b, h) do { _Pragma("unroll") for (int n = 0; n < 2; ++n) _Pragma("unroll") for (int k = 0; k < 2; ++k) dst[n][k] = *(const LAS bf16x8*)(lds + PG8_SB(b, h) + boff + n * 2048 + k * 1024); } while (0)
; template <class Epi, bool AFTER = false>
; __device__ __forceinline__ void gemm_phase(LAS unsigned char* lds, const Gemm g, const StaticOrder& S, const Epi& E) {
;     ...
;             PG8_LDB(B0, 0, 0); PG8_SCHED; PG8_LDA(At, 0, 0); PG8_STAGE(PG8_SA(1, 1), a1 + hstep, voffA);
;             PG8_WAIT_L(8); PG8_BAR; PG8_WAIT_L(0); PG8_MMA(0, 0, At, B0); PG8_BAR; PG8_SCHED;
;             PG8_LDB(B1, 0, 1); PG8_STAGE(PG8_SB(0, 0), b2, voffB);
;             PG8_BAR; PG8_WAIT_L(0); PG8_MMA(0, 1, At, B1); PG8_BAR;
;             PG8_LDA(At, 0, 1); PG8_STAGE(PG8_SA(0, 0), a2, voffA);
;             PG8_BAR; PG8_WAIT_L(0); PG8_MMA(1, 0, At, B0); PG8_BAR; PG8_SCHED;
.LBB0_420:
	ds_read_b128 v[158:161], v151
	ds_read_b128 v[162:165], v151 offset:1024
	ds_read_b128 v[166:169], v151 offset:2048
	ds_read_b128 v[170:173], v151 offset:3072
	s_add_u32 s24, s22, 0xfffc0080
	s_addc_u32 s25, s23, -1
	s_cmp_eq_u32 s29, 12
	s_cselect_b32 s27, s5, s25
	s_cselect_b32 s26, s7, s24
	s_cselect_b32 s25, s8, s28
	s_cselect_b32 s24, s15, s17
	v_lshl_add_u64 v[148:149], s[22:23], 0, v[140:141]
	s_add_i32 m0, s43, 0xc000
	ds_read_b128 v[174:177], v152
	ds_read_b128 v[178:181], v152 offset:1024
	ds_read_b128 v[182:185], v152 offset:2048
	ds_read_b128 v[186:189], v152 offset:3072
	ds_read_b128 v[192:195], v152 offset:4096
	ds_read_b128 v[196:199], v152 offset:5120
	ds_read_b128 v[200:203], v152 offset:6144
	ds_read_b128 v[204:207], v152 offset:7168
	global_load_lds_dwordx4 v[148:149], off
	v_lshl_add_u64 v[148:149], s[22:23], 0, v[142:143]
	s_add_i32 m0, s43, 0xe000
	s_nop 0
	global_load_lds_dwordx4 v[148:149], off
	s_waitcnt lgkmcnt(8)
	s_barrier
	s_waitcnt lgkmcnt(0)
	s_setprio 1
	s_waitcnt lgkmcnt(0)
	v_mfma_f32_16x16x32_bf16 v[124:127], v[158:161], v[174:177], v[124:127]
	v_mfma_f32_16x16x32_bf16 v[120:123], v[166:169], v[174:177], v[120:123]
	v_mfma_f32_16x16x32_bf16 v[108:111], v[158:161], v[182:185], v[108:111]
	v_mfma_f32_16x16x32_bf16 v[104:107], v[166:169], v[182:185], v[104:107]
	v_mfma_f32_16x16x32_bf16 v[92:95], v[158:161], v[192:195], v[92:95]
	v_mfma_f32_16x16x32_bf16 v[88:91], v[166:169], v[192:195], v[88:91]
	v_mfma_f32_16x16x32_bf16 v[76:79], v[158:161], v[200:203], v[76:79]
	v_mfma_f32_16x16x32_bf16 v[72:75], v[166:169], v[200:203], v[72:75]
	v_mfma_f32_16x16x32_bf16 v[124:127], v[162:165], v[178:181], v[124:127]
	v_mfma_f32_16x16x32_bf16 v[120:123], v[170:173], v[178:181], v[120:123]
	v_mfma_f32_16x16x32_bf16 v[108:111], v[162:165], v[186:189], v[108:111]
	v_mfma_f32_16x16x32_bf16 v[104:107], v[170:173], v[186:189], v[104:107]
	v_mfma_f32_16x16x32_bf16 v[92:95], v[162:165], v[196:199], v[92:95]
	v_mfma_f32_16x16x32_bf16 v[88:91], v[170:173], v[196:199], v[88:91]
	v_mfma_f32_16x16x32_bf16 v[76:79], v[162:165], v[204:207], v[76:79]
	v_mfma_f32_16x16x32_bf16 v[72:75], v[170:173], v[204:207], v[72:75]
	s_setprio 0
	s_barrier
	s_add_i32 s30, s58, s42
	v_lshl_add_u64 v[148:149], s[24:25], 0, v[130:131]
	s_mov_b32 m0, s30
	ds_read_b128 v[208:211], v153
	ds_read_b128 v[214:217], v153 offset:1024
	ds_read_b128 v[218:221], v153 offset:2048
	ds_read_b128 v[222:225], v153 offset:3072
	global_load_lds_dwordx4 v[148:149], off
	v_lshl_add_u64 v[226:227], s[24:25], 0, v[134:135]
	s_add_i32 m0, s30, 0x2000
	s_nop 0
	global_load_lds_dwordx4 v[226:227], off
	s_barrier
	s_waitcnt lgkmcnt(0)
	s_setprio 1
	s_waitcnt lgkmcnt(0)
	v_mfma_f32_16x16x32_bf16 v[116:119], v[208:211], v[174:177], v[116:119]
	v_mfma_f32_16x16x32_bf16 v[112:115], v[218:221], v[174:177], v[112:115]
	v_mfma_f32_16x16x32_bf16 v[100:103], v[208:211], v[182:185], v[100:103]
	v_mfma_f32_16x16x32_bf16 v[96:99], v[218:221], v[182:185], v[96:99]
	v_mfma_f32_16x16x32_bf16 v[84:87], v[208:211], v[192:195], v[84:87]
	v_mfma_f32_16x16x32_bf16 v[80:83], v[218:221], v[192:195], v[80:83]
	v_mfma_f32_16x16x32_bf16 v[68:71], v[208:211], v[200:203], v[68:71]
	v_mfma_f32_16x16x32_bf16 v[64:67], v[218:221], v[200:203], v[64:67]
	v_mfma_f32_16x16x32_bf16 v[116:119], v[214:217], v[178:181], v[116:119]
	v_mfma_f32_16x16x32_bf16 v[112:115], v[222:225], v[178:181], v[112:115]
	v_mfma_f32_16x16x32_bf16 v[100:103], v[214:217], v[186:189], v[100:103]
	v_mfma_f32_16x16x32_bf16 v[96:99], v[222:225], v[186:189], v[96:99]
	v_mfma_f32_16x16x32_bf16 v[84:87], v[214:217], v[196:199], v[84:87]
	v_mfma_f32_16x16x32_bf16 v[80:83], v[222:225], v[196:199], v[80:83]
	v_mfma_f32_16x16x32_bf16 v[68:71], v[214:217], v[204:207], v[68:71]
	v_mfma_f32_16x16x32_bf16 v[64:67], v[222:225], v[204:207], v[64:67]
	s_setprio 0
	s_mov_b32 m0, s43
	v_lshl_add_u64 v[228:229], s[26:27], 0, v[128:129]
	s_barrier
	ds_read_b128 v[174:177], v152 offset:16384
	ds_read_b128 v[178:181], v152 offset:17408
	ds_read_b128 v[182:185], v152 offset:18432
	ds_read_b128 v[186:189], v152 offset:19456
	ds_read_b128 v[192:195], v152 offset:20480
	ds_read_b128 v[196:199], v152 offset:21504
	ds_read_b128 v[200:203], v152 offset:22528
	ds_read_b128 v[204:207], v152 offset:23552
	global_load_lds_dwordx4 v[228:229], off
	v_lshl_add_u64 v[230:231], s[26:27], 0, v[132:133]
	s_mov_b32 m0, s44
	s_nop 0
	global_load_lds_dwordx4 v[230:231], off
	s_barrier
	s_waitcnt lgkmcnt(0)
	s_setprio 1
	s_waitcnt lgkmcnt(0)
	v_mfma_f32_16x16x32_bf16 v[60:63], v[158:161], v[174:177], v[60:63]
	v_mfma_f32_16x16x32_bf16 v[56:59], v[166:169], v[174:177], v[56:59]
	v_mfma_f32_16x16x32_bf16 v[44:47], v[158:161], v[182:185], v[44:47]
	v_mfma_f32_16x16x32_bf16 v[40:43], v[166:169], v[182:185], v[40:43]
	v_mfma_f32_16x16x32_bf16 v[28:31], v[158:161], v[192:195], v[28:31]
	v_mfma_f32_16x16x32_bf16 v[24:27], v[166:169], v[192:195], v[24:27]
	v_mfma_f32_16x16x32_bf16 v[12:15], v[158:161], v[200:203], v[12:15]
	v_mfma_f32_16x16x32_bf16 v[8:11], v[166:169], v[200:203], v[8:11]
	v_mfma_f32_16x16x32_bf16 v[60:63], v[162:165], v[178:181], v[60:63]
	v_mfma_f32_16x16x32_bf16 v[56:59], v[170:173], v[178:181], v[56:59]
	v_mfma_f32_16x16x32_bf16 v[44:47], v[162:165], v[186:189], v[44:47]
	v_mfma_f32_16x16x32_bf16 v[40:43], v[170:173], v[186:189], v[40:43]
	v_mfma_f32_16x16x32_bf16 v[28:31], v[162:165], v[196:199], v[28:31]
	v_mfma_f32_16x16x32_bf16 v[24:27], v[170:173], v[196:199], v[24:27]
	v_mfma_f32_16x16x32_bf16 v[12:15], v[162:165], v[204:207], v[12:15]
	v_mfma_f32_16x16x32_bf16 v[8:11], v[170:173], v[204:207], v[8:11]
	s_setprio 0
	s_barrier
; #define PG8_STAGE(bufoff, gbase, voff) do { _Pragma("unroll") for (int _i = 0; _i < 2; ++_i) \
;         __builtin_amdgcn_global_load_lds((const unsigned*)((const char*)(gbase) + (voff)[_i]), (LAS unsigned*)(lds + (bufoff) + ldsw + _i * 8192), 16, 0, 0); } while (0)
; #define PG8_LDA(dst, b, h) do { _Pragma("unroll") for (int m = 0; m < 4; ++m) _Pragma("unroll") for (int k = 0; k < 2; ++k) dst[m][k] = *(const LAS bf16x8*)(lds + PG8_SA(b, h) + aoff + m * 2048 + k * 1024); } while (0)
; #define PG8_LDB(dst, b, h) do { _Pragma("unroll") for (int n = 0; n < 2; ++n) _Pragma("unroll") for (int k = 0; k < 2; ++k) dst[n][k] = *(const LAS bf16x8*)(lds + PG8_SB(b, h) + boff + n * 2048 + k * 1024); } while (0)
; #define PG8_MMA(ai, bj, At, Bt) do { __builtin_amdgcn_s_setprio(1); _Pragma("unroll") for (int m = 0; m < 4; ++m) _Pragma("unroll") for (int n = 0; n < 2; ++n) _Pragma("unroll") for (int k = 0; k < 2; ++k) \
;         acc[ai][bj][m][n] = __builtin_amdgcn_mfma_f32_16x16x32_bf16(Bt[n][k], At[m][k], acc[ai][bj][m][n], 0, 0, 0); __builtin_amdgcn_s_setprio(0); } while (0)
; #define PG8_WAIT_V(n) asm volatile("s_waitcnt vmcnt(" #n ")" ::: "memory")
; #define PG8_WAIT_L(n) asm volatile("s_waitcnt lgkmcnt(" #n ")" ::: "memory")
; #define PG8_BAR __builtin_amdgcn_s_barrier()
; #define PG8_SCHED __builtin_amdgcn_sched_barrier(0)
; #define PG8_LDA(dst, b, h) do { _Pragma("unroll") for (int m = 0; m < 4; ++m) _Pragma("unroll") for (int k = 0; k < 2; ++k) dst[m][k] = *(const LAS bf16x8*)(lds + PG8_SA(b, h) + aoff + m * 2048 + k * 1024); } while (0)
; #define PG8_BAR __builtin_amdgcn_s_barrier()
; template <class Epi, bool AFTER = false>
; __device__ __forceinline__ void gemm_phase(LAS unsigned char* lds, const Gemm g, const StaticOrder& S, const Epi& E) {
;     ...
;             PG8_STAGE(PG8_SB(0, 1), b2 + hstep, voffB);
;             PG8_WAIT_V(6); PG8_BAR; PG8_MMA(1, 1, At, B1); PG8_BAR;
;             PG8_LDB(B0, 1, 0); PG8_SCHED; PG8_LDA(At, 1, 0); PG8_STAGE(PG8_SA(0, 1), a2 + hstep, voffA);
;             PG8_WAIT_L(8); PG8_BAR; PG8_WAIT_L(0); PG8_MMA(0, 0, At, B0); PG8_BAR; PG8_SCHED;
;             PG8_LDB(B1, 1, 1); PG8_STAGE(PG8_SB(1, 0), b3, voffB);
;             PG8_BAR; PG8_WAIT_L(0); PG8_MMA(0, 1, At, B1); PG8_BAR;
;             PG8_LDA(At, 1, 1); PG8_STAGE(PG8_SA(1, 0), a3, voffA);
;             PG8_BAR; PG8_WAIT_L(0); PG8_MMA(1, 0, At, B0); PG8_BAR; PG8_SCHED;
	s_add_u32 s30, s24, 0x40000
	s_addc_u32 s31, s25, 0
	s_add_i32 s34, s59, s42
	v_lshl_add_u64 v[158:159], s[30:31], 0, v[130:131]
	s_mov_b32 m0, s34
	s_nop 0
	global_load_lds_dwordx4 v[158:159], off
	v_lshl_add_u64 v[158:159], s[30:31], 0, v[134:135]
	s_add_i32 m0, s34, 0x2000
	s_nop 0
	global_load_lds_dwordx4 v[158:159], off
	s_waitcnt vmcnt(6)
	s_barrier
	s_setprio 1
	v_mfma_f32_16x16x32_bf16 v[52:55], v[208:211], v[174:177], v[52:55]
	v_mfma_f32_16x16x32_bf16 v[48:51], v[218:221], v[174:177], v[48:51]
	v_mfma_f32_16x16x32_bf16 v[36:39], v[208:211], v[182:185], v[36:39]
	v_mfma_f32_16x16x32_bf16 v[32:35], v[218:221], v[182:185], v[32:35]
	v_mfma_f32_16x16x32_bf16 v[20:23], v[208:211], v[192:195], v[20:23]
	v_mfma_f32_16x16x32_bf16 v[16:19], v[218:221], v[192:195], v[16:19]
	v_mfma_f32_16x16x32_bf16 v[4:7], v[208:211], v[200:203], v[4:7]
	v_mfma_f32_16x16x32_bf16 v[0:3], v[218:221], v[200:203], v[0:3]
	v_mfma_f32_16x16x32_bf16 v[52:55], v[214:217], v[178:181], v[52:55]
	v_mfma_f32_16x16x32_bf16 v[48:51], v[222:225], v[178:181], v[48:51]
	v_mfma_f32_16x16x32_bf16 v[36:39], v[214:217], v[186:189], v[36:39]
	v_mfma_f32_16x16x32_bf16 v[32:35], v[222:225], v[186:189], v[32:35]
	v_mfma_f32_16x16x32_bf16 v[20:23], v[214:217], v[196:199], v[20:23]
	v_mfma_f32_16x16x32_bf16 v[16:19], v[222:225], v[196:199], v[16:19]
	v_mfma_f32_16x16x32_bf16 v[4:7], v[214:217], v[204:207], v[4:7]
	v_mfma_f32_16x16x32_bf16 v[0:3], v[222:225], v[204:207], v[0:3]
	s_setprio 0
	s_add_i32 s30, 0, 0x18000
	v_add_u32_e32 v136, s30, v150
	s_barrier
	ds_read_b128 v[158:161], v136
	ds_read_b128 v[162:165], v136 offset:1024
	ds_read_b128 v[166:169], v136 offset:2048
	ds_read_b128 v[170:173], v136 offset:3072
	s_add_u32 s26, s26, 0x40000
	s_addc_u32 s27, s27, 0
	s_mov_b32 m0, s45
	v_lshl_add_u64 v[208:209], s[26:27], 0, v[128:129]
	ds_read_b128 v[174:177], v152 offset:32768
	ds_read_b128 v[178:181], v152 offset:33792
	ds_read_b128 v[182:185], v152 offset:34816
	ds_read_b128 v[186:189], v152 offset:35840
	ds_read_b128 v[192:195], v152 offset:36864
	ds_read_b128 v[196:199], v152 offset:37888
	ds_read_b128 v[200:203], v152 offset:38912
	ds_read_b128 v[204:207], v152 offset:39936
	global_load_lds_dwordx4 v[208:209], off
	v_lshl_add_u64 v[208:209], s[26:27], 0, v[132:133]
	s_mov_b32 m0, s46
	s_nop 0
	global_load_lds_dwordx4 v[208:209], off
	s_waitcnt lgkmcnt(8)
	s_barrier
	s_waitcnt lgkmcnt(0)
	s_setprio 1
	s_waitcnt lgkmcnt(0)
	v_mfma_f32_16x16x32_bf16 v[124:127], v[158:161], v[174:177], v[124:127]
	v_mfma_f32_16x16x32_bf16 v[120:123], v[166:169], v[174:177], v[120:123]
	v_mfma_f32_16x16x32_bf16 v[108:111], v[158:161], v[182:185], v[108:111]
	v_mfma_f32_16x16x32_bf16 v[104:107], v[166:169], v[182:185], v[104:107]
	v_mfma_f32_16x16x32_bf16 v[92:95], v[158:161], v[192:195], v[92:95]
	v_mfma_f32_16x16x32_bf16 v[88:91], v[166:169], v[192:195], v[88:91]
	v_mfma_f32_16x16x32_bf16 v[76:79], v[158:161], v[200:203], v[76:79]
	v_mfma_f32_16x16x32_bf16 v[72:75], v[166:169], v[200:203], v[72:75]
	v_mfma_f32_16x16x32_bf16 v[124:127], v[162:165], v[178:181], v[124:127]
	v_mfma_f32_16x16x32_bf16 v[120:123], v[170:173], v[178:181], v[120:123]
	v_mfma_f32_16x16x32_bf16 v[108:111], v[162:165], v[186:189], v[108:111]
	v_mfma_f32_16x16x32_bf16 v[104:107], v[170:173], v[186:189], v[104:107]
	v_mfma_f32_16x16x32_bf16 v[92:95], v[162:165], v[196:199], v[92:95]
	v_mfma_f32_16x16x32_bf16 v[88:91], v[170:173], v[196:199], v[88:91]
	v_mfma_f32_16x16x32_bf16 v[76:79], v[162:165], v[204:207], v[76:79]
	v_mfma_f32_16x16x32_bf16 v[72:75], v[170:173], v[204:207], v[72:75]
	s_setprio 0
	s_barrier
	s_add_i32 s26, 0, 0x1c000
	s_add_i32 s27, s30, s42
	v_add_u32_e32 v136, s26, v150
	v_lshl_add_u64 v[148:149], v[148:149], 0, s[10:11]
	s_mov_b32 m0, s27
	ds_read_b128 v[208:211], v136
	ds_read_b128 v[214:217], v136 offset:1024
	ds_read_b128 v[218:221], v136 offset:2048
	ds_read_b128 v[222:225], v136 offset:3072
	global_load_lds_dwordx4 v[148:149], off
	v_lshl_add_u64 v[148:149], v[226:227], 0, s[10:11]
	s_add_i32 m0, s27, 0x2000
	s_nop 0
	global_load_lds_dwordx4 v[148:149], off
	s_barrier
	s_waitcnt lgkmcnt(0)
	s_setprio 1
	s_waitcnt lgkmcnt(0)
	v_mfma_f32_16x16x32_bf16 v[116:119], v[208:211], v[174:177], v[116:119]
	v_mfma_f32_16x16x32_bf16 v[112:115], v[218:221], v[174:177], v[112:115]
	v_mfma_f32_16x16x32_bf16 v[100:103], v[208:211], v[182:185], v[100:103]
	v_mfma_f32_16x16x32_bf16 v[96:99], v[218:221], v[182:185], v[96:99]
	v_mfma_f32_16x16x32_bf16 v[84:87], v[208:211], v[192:195], v[84:87]
	v_mfma_f32_16x16x32_bf16 v[80:83], v[218:221], v[192:195], v[80:83]
	v_mfma_f32_16x16x32_bf16 v[68:71], v[208:211], v[200:203], v[68:71]
	v_mfma_f32_16x16x32_bf16 v[64:67], v[218:221], v[200:203], v[64:67]
	v_mfma_f32_16x16x32_bf16 v[116:119], v[214:217], v[178:181], v[116:119]
	v_mfma_f32_16x16x32_bf16 v[112:115], v[222:225], v[178:181], v[112:115]
	v_mfma_f32_16x16x32_bf16 v[100:103], v[214:217], v[186:189], v[100:103]
	v_mfma_f32_16x16x32_bf16 v[96:99], v[222:225], v[186:189], v[96:99]
	v_mfma_f32_16x16x32_bf16 v[84:87], v[214:217], v[196:199], v[84:87]
	v_mfma_f32_16x16x32_bf16 v[80:83], v[222:225], v[196:199], v[80:83]
	v_mfma_f32_16x16x32_bf16 v[68:71], v[214:217], v[204:207], v[68:71]
	v_mfma_f32_16x16x32_bf16 v[64:67], v[222:225], v[204:207], v[64:67]
	s_setprio 0
	s_mov_b32 m0, s54
	v_lshl_add_u64 v[148:149], v[228:229], 0, s[10:11]
	s_barrier
; __device__ __forceinline__ void st_wt16(void* p, u32x4 v) { asm volatile("global_store_dwordx4 %0, %1, off sc1\n\ts_nop 1" : : "v"(p), "v"(v) : "memory"); }
; template <class Epi, bool AFTER = false>
; __device__ __forceinline__ void gemm_phase(LAS unsigned char* lds, const Gemm g, const StaticOrder& S, const Epi& E) {
;     ...
;             PG8_STAGE(PG8_SB(1, 1), b3 + hstep, voffB);
;             PG8_WAIT_V(6); PG8_BAR; PG8_MMA(1, 1, At, B1); PG8_BAR;
;         }
;         if constexpr (!AFTER) E(acc, cur, wr, wc, fr, fq);
;     __device__ __forceinline__ void operator()(const f32x4 (&acc)[2][2][4][2], const pg8::Unit& u, int wr, int wc, int fr, int fq) const {
;         const int pn = u.pn; const int row0 = u.pm * 256 + wr * 64 + fr; const int cl = wc * 32 + 8 * fq;
; #pragma unroll
;         for (int ai = 0; ai < 2; ++ai)
; #pragma unroll
;             for (int m = 0; m < 4; ++m) {
;                 const int row = row0 + ai * 128 + m * 16;
;                 u32x4 w0, w1;
;                 w0.x = cvt_pk_bf16(acc[ai][0][m][0][0], acc[ai][0][m][0][1]); w0.y = cvt_pk_bf16(acc[ai][0][m][0][2], acc[ai][0][m][0][3]);
;                 w0.z = cvt_pk_bf16(acc[ai][0][m][1][0], acc[ai][0][m][1][1]); w0.w = cvt_pk_bf16(acc[ai][0][m][1][2], acc[ai][0][m][1][3]);
;                 w1.x = cvt_pk_bf16(acc[ai][1][m][0][0], acc[ai][1][m][0][1]); w1.y = cvt_pk_bf16(acc[ai][1][m][0][2], acc[ai][1][m][0][3]);
;                 w1.z = cvt_pk_bf16(acc[ai][1][m][1][0], acc[ai][1][m][1][1]); w1.w = cvt_pk_bf16(acc[ai][1][m][1][2], acc[ai][1][m][1][3]);
;                 if (pn < 6) { bf16_t* rp = QZ + (size_t)row * QZ_LD + pn * 256 + cl; st_wt16(rp, w0); st_wt16_o256(rp, w1); }
;                 else if (pn < 18) {
;                     bf16_t* base = (pn < 12) ? KA : VA; const int c = (pn < 12 ? pn - 6 : pn - 12) * 256 + cl;
;                     const int b = row >> 11, pos = row & 2047;
; #pragma unroll
;                     for (int bj = 0; bj < 2; ++bj) {
;                         const int cc = c + bj * 128; const int g = cc >> 9, h = (cc >> 7) & 3, e = cc & 127; const int lg = 2 * g;
;                         const int rr = pos & ((1 << lg) - 1), j = pos >> lg;
;                         const size_t off = (size_t)g * ((size_t)T_TOK * 512) + ((size_t)((((b * 4 + h) << lg) + rr) * (2048 >> lg) + j)) * 128 + e;
;                         st_wt16(base + off, bj == 0 ? w0 : w1);
	ds_read_b128 v[174:177], v152 offset:49152
	ds_read_b128 v[178:181], v152 offset:50176
	ds_read_b128 v[182:185], v152 offset:51200
	ds_read_b128 v[186:189], v152 offset:52224
	ds_read_b128 v[192:195], v152 offset:53248
	ds_read_b128 v[196:199], v152 offset:54272
	ds_read_b128 v[200:203], v152 offset:55296
	ds_read_b128 v[204:207], v152 offset:56320
	global_load_lds_dwordx4 v[148:149], off
	v_lshl_add_u64 v[148:149], v[230:231], 0, s[10:11]
	s_mov_b32 m0, s55
	s_nop 0
	global_load_lds_dwordx4 v[148:149], off
	s_barrier
	s_waitcnt lgkmcnt(0)
	s_setprio 1
	s_waitcnt lgkmcnt(0)
	v_mfma_f32_16x16x32_bf16 v[60:63], v[158:161], v[174:177], v[60:63]
	v_mfma_f32_16x16x32_bf16 v[56:59], v[166:169], v[174:177], v[56:59]
	v_mfma_f32_16x16x32_bf16 v[44:47], v[158:161], v[182:185], v[44:47]
	v_mfma_f32_16x16x32_bf16 v[40:43], v[166:169], v[182:185], v[40:43]
	v_mfma_f32_16x16x32_bf16 v[28:31], v[158:161], v[192:195], v[28:31]
	v_mfma_f32_16x16x32_bf16 v[24:27], v[166:169], v[192:195], v[24:27]
	v_mfma_f32_16x16x32_bf16 v[12:15], v[158:161], v[200:203], v[12:15]
	v_mfma_f32_16x16x32_bf16 v[8:11], v[166:169], v[200:203], v[8:11]
	v_mfma_f32_16x16x32_bf16 v[60:63], v[162:165], v[178:181], v[60:63]
	v_mfma_f32_16x16x32_bf16 v[56:59], v[170:173], v[178:181], v[56:59]
	v_mfma_f32_16x16x32_bf16 v[44:47], v[162:165], v[186:189], v[44:47]
	v_mfma_f32_16x16x32_bf16 v[40:43], v[170:173], v[186:189], v[40:43]
	v_mfma_f32_16x16x32_bf16 v[28:31], v[162:165], v[196:199], v[28:31]
	v_mfma_f32_16x16x32_bf16 v[24:27], v[170:173], v[196:199], v[24:27]
	v_mfma_f32_16x16x32_bf16 v[12:15], v[162:165], v[204:207], v[12:15]
	v_mfma_f32_16x16x32_bf16 v[8:11], v[170:173], v[204:207], v[8:11]
	s_setprio 0
	s_barrier
	s_add_u32 s24, s24, 0x40080
	s_addc_u32 s25, s25, 0
	s_add_i32 s26, s26, s42
	v_lshl_add_u64 v[148:149], s[24:25], 0, v[130:131]
	s_mov_b32 m0, s26
	s_nop 0
	global_load_lds_dwordx4 v[148:149], off
	v_lshl_add_u64 v[148:149], s[24:25], 0, v[134:135]
	s_add_i32 m0, s26, 0x2000
	s_nop 0
	global_load_lds_dwordx4 v[148:149], off
	s_waitcnt vmcnt(6)
	s_barrier
	s_setprio 1
	v_mfma_f32_16x16x32_bf16 v[52:55], v[208:211], v[174:177], v[52:55]
	v_mfma_f32_16x16x32_bf16 v[48:51], v[218:221], v[174:177], v[48:51]
	v_mfma_f32_16x16x32_bf16 v[36:39], v[208:211], v[182:185], v[36:39]
	v_mfma_f32_16x16x32_bf16 v[32:35], v[218:221], v[182:185], v[32:35]
	v_mfma_f32_16x16x32_bf16 v[20:23], v[208:211], v[192:195], v[20:23]
	v_mfma_f32_16x16x32_bf16 v[16:19], v[218:221], v[192:195], v[16:19]
	v_mfma_f32_16x16x32_bf16 v[4:7], v[208:211], v[200:203], v[4:7]
	v_mfma_f32_16x16x32_bf16 v[0:3], v[218:221], v[200:203], v[0:3]
	v_mfma_f32_16x16x32_bf16 v[52:55], v[214:217], v[178:181], v[52:55]
	v_mfma_f32_16x16x32_bf16 v[48:51], v[222:225], v[178:181], v[48:51]
	v_mfma_f32_16x16x32_bf16 v[36:39], v[214:217], v[186:189], v[36:39]
	v_mfma_f32_16x16x32_bf16 v[32:35], v[222:225], v[186:189], v[32:35]
	v_mfma_f32_16x16x32_bf16 v[20:23], v[214:217], v[196:199], v[20:23]
	v_mfma_f32_16x16x32_bf16 v[16:19], v[222:225], v[196:199], v[16:19]
	v_mfma_f32_16x16x32_bf16 v[4:7], v[214:217], v[204:207], v[4:7]
	v_mfma_f32_16x16x32_bf16 v[0:3], v[222:225], v[204:207], v[0:3]
	s_setprio 0
	s_add_i32 s29, s29, 2
	s_add_u32 s22, s22, 0x100
	s_addc_u32 s23, s23, 0
	s_add_u32 s17, s17, 0x100
	s_addc_u32 s28, s28, 0
	s_cmp_gt_u32 s29, 13
	s_barrier
	s_cbranch_scc0 .LBB0_420
	v_readfirstlane_b32 s98, v212
	s_nop 3
	s_cmp_ge_u32 s98, 0x100
	s_cbranch_scc0 .Lep_p4
	s_setprio 1
.Lep_p4:
	s_lshl_b32 s5, s6, 8
	s_add_i32 s5, s5, s53
	s_cmp_gt_i32 s4, 5
	s_cselect_b64 s[34:35], -1, 0
	s_cmp_gt_u32 s4, 17
	s_cselect_b64 s[36:37], -1, 0
	s_cmp_gt_u32 s4, 19
	s_cselect_b64 s[30:31], -1, 0
	s_lshl_b32 s22, s4, 8
	s_add_i32 s8, s22, 0xffffec00
	s_cmp_lt_u32 s4, 12
	s_cselect_b64 s[24:25], -1, 0
	s_and_b64 s[6:7], s[24:25], exec
	s_cselect_b32 s6, -6, -12
	s_add_i32 s7, s6, s4
	s_lshl_b32 s4, s4, 1
	s_and_b32 s15, s7, -2
	s_and_b32 s62, s4, 2
	s_lshl_b32 s4, -1, s15
	s_ashr_i32 s6, s7, 1
	s_not_b32 s61, s4
	s_ashr_i32 s4, s5, 9
	s_ashr_i32 s7, s6, 31
	s_and_b32 s4, s4, -4
	v_or_b32_e32 v148, s5, v139
	s_mov_b32 s28, s22
	s_mov_b32 s29, s9
	s_lshr_b32 s17, 0x800, s15
	s_lshl_b64 s[26:27], s[6:7], 24
	s_or_b32 s63, s4, s62
	v_cvt_pk_bf16_f32 v124, v124, v125
	v_cvt_pk_bf16_f32 v125, v126, v127
	v_cvt_pk_bf16_f32 v126, v120, v121
	v_cvt_pk_bf16_f32 v127, v122, v123
	v_cvt_pk_bf16_f32 v116, v116, v117
	v_cvt_pk_bf16_f32 v117, v118, v119
	v_cvt_pk_bf16_f32 v118, v112, v113
	v_cvt_pk_bf16_f32 v119, v114, v115
	s_mov_b64 s[4:5], -1
	s_and_b64 vcc, exec, s[34:35]
	s_cbranch_vccz .LBB0_431
	s_and_b64 vcc, exec, s[36:37]
	s_cbranch_vccz .LBB0_428
	v_ashrrev_i32_e32 v149, 31, v148
	v_lshlrev_b64 v[112:113], 12, v[148:149]
	s_and_b64 vcc, exec, s[30:31]
	s_cbranch_vccz .LBB0_425
	v_lshl_add_u64 v[114:115], s[94:95], 0, v[112:113]
	v_lshl_add_u64 v[114:115], s[8:9], 1, v[114:115]
	v_lshlrev_b32_e32 v136, 1, v138
	v_lshl_add_u64 v[114:115], v[114:115], 0, v[136:137]
	global_store_dwordx4 v[114:115], v[124:127], off sc1
	s_nop 1
	global_store_dwordx4 v[114:115], v[116:119], off offset:256 sc1
	s_nop 1
	s_mov_b64 s[4:5], 0
